# gate|up phase re-split with uneven conversion shares (workgroups with 4 tiles convert 118 tiles, with 5 tiles 63)
# speedup vs baseline: 1.0055x; 1.0055x over previous
; #define LAS __attribute__((address_space(3)))
; #define KP() ({ KArgs kp_ = kp0; asm volatile("" : "+s"(kp_)); kp_; })
; #define G_ ({ int g__ = (int)gridDim.x; asm volatile("" : "+s"(g__)); g__; })
; #define c_ ({ int c__ = (int)blockIdx.x; asm volatile("" : "+s"(c__)); c__; })
; template <class KA> __device__ __forceinline__ void convert_range(KA a, LAS unsigned char* lds, int t_lo, int t_hi, int rank, int nrank) {
;     int tid_ = threadIdx.x; asm volatile("" : "+v"(tid_));
;     const int lane = tid_ & 63, wave = __builtin_amdgcn_readfirstlane(tid_ >> 6); LAS unsigned short* tl = (LAS unsigned short*)(lds + wave * 16384);
;     const int stride = nrank * 8; int it = t_lo + rank * 8 + wave;
;     if (it >= t_hi) return;
; __global__ void __launch_bounds__(512, 2) mega(MegaArgs a) {
;     ...
;             { const int rem = ((T_SEQ / 256) * (NGU / 256)) % G_, q = 3 * l + (half ? 2 : 0), hi = cvt_slot_hi(q) < CVT_TOTAL ? cvt_slot_hi(q) : CVT_TOTAL;
;               if (!(hf & 2) && rem && c_ >= rem && cvt_slot_lo(q) < hi) { KArgs kq = KP(); convert_range(kq, lds, cvt_slot_lo(q), hi, c_ - rem, G_ - rem); } }
.LBB0_308:
	s_mov_b32 s0, s21
	s_abs_i32 s0, s0
	v_cvt_f32_u32_e32 v1, s0
	s_sub_i32 s1, 0, s0
	v_rcp_iflag_f32_e32 v1, v1
	s_nop 0
	v_mul_f32_e32 v1, 0x4f7ffffe, v1
	v_cvt_u32_f32_e32 v1, v1
	s_nop 0
	v_readfirstlane_b32 s2, v1
	s_mul_i32 s1, s1, s2
	s_mul_hi_u32 s1, s2, s1
	s_add_i32 s2, s2, s1
	s_mul_hi_u32 s1, s2, 0x560
	s_mul_i32 s1, s1, s0
	s_sub_i32 s1, 0x560, s1
	s_sub_i32 s2, s1, s0
	s_cmp_ge_u32 s1, s0
	s_cselect_b32 s1, s2, s1
	s_sub_i32 s2, s1, s0
	s_cmp_ge_u32 s1, s0
	v_readlane_b32 s0, v251, 24
	s_cselect_b32 s44, s2, s1
	s_movk_i32 s44, 0xa0
	s_bitcmp1_b32 s0, 1
	s_cselect_b64 s[0:1], -1, 0
	s_cmp_eq_u32 s44, 0
	s_cselect_b64 s[4:5], -1, 0
	s_or_b64 s[0:1], s[0:1], s[4:5]
	s_and_b64 vcc, exec, s[0:1]
	s_cbranch_vccnz .LBB0_496
	v_readlane_b32 s0, v251, 22
	v_readlane_b32 s1, v251, 23
	s_mul_i32 s0, s0, 3
	s_lshl_b32 s1, s52, 1
	s_add_i32 s1, s1, s0
	s_mul_hi_i32 s0, s1, 0x55555556
	s_lshr_b32 s2, s0, 31
	s_add_i32 s0, s0, s2
	s_mul_i32 s2, s0, 3
	s_sub_i32 s1, s1, s2
	s_cmp_eq_u32 s1, 1
	s_movk_i32 s2, 0x2580
	s_movk_i32 s4, 0x1ce8
	s_cselect_b32 s2, s2, 0x4268
	s_cselect_b32 s4, s4, 0x2580
	s_cmp_lg_u32 s1, 0
	s_mulk_i32 s0, 0x67e8
	s_cselect_b32 s1, s2, 0
	s_add_i32 s2, s0, s1
	s_addk_i32 s2, 0x2200
	s_add_i32 s0, s2, s4
	s_min_i32 s26, s0, 0x1a500
	s_mov_b32 s0, s67
	s_cmp_ge_i32 s0, s44
	s_cselect_b64 s[0:1], -1, 0
	s_cmp_lt_i32 s2, s26
	s_cselect_b64 s[4:5], -1, 0
	s_and_b64 s[0:1], s[0:1], s[4:5]
	s_andn2_b64 vcc, exec, s[0:1]
	s_cbranch_vccnz .LBB0_496
	s_mov_b64 s[0:1], s[70:71]
	s_mov_b32 s4, s67
	s_sub_i32 s4, s4, s44
	s_mov_b32 s45, s21
	s_cmp_lt_u32 s4, 32
	s_cbranch_scc1 .Lrb1_B
	s_sub_i32 s4, s4, 32
	s_movk_i32 s44, 0xc0
	s_addk_i32 s2, 0x7e0
	s_branch .Lrb1_done
.Lrb1_B:
	s_movk_i32 s45, 0xc0
	s_add_i32 s27, s2, 0x7e0
	s_min_i32 s26, s26, s27
.Lrb1_done:
	v_mov_b32_e32 v1, v0
	s_lshl_b32 s4, s4, 3
	v_readfirstlane_b32 s47, v1
	s_ashr_i32 s46, s47, 6
	s_add_i32 s2, s4, s2
	s_add_i32 s27, s2, s46
	s_cmp_ge_i32 s27, s26
	s_cbranch_scc1 .LBB0_496
	s_mul_hi_i32 s2, s27, 0x9baade8f
	s_add_i32 s2, s2, s27
	s_load_dwordx2 s[4:5], s[0:1], 0xd8
	s_waitcnt lgkmcnt(0)
	s_lshr_b32 s6, s2, 31
	s_ashr_i32 s2, s2, 14
	s_add_i32 s30, s2, s6
	s_mul_i32 s42, s30, 0xffff96c0
	s_add_i32 s42, s42, s27
	s_add_u32 s53, s4, 0x200000
	s_addc_u32 s54, s5, 0
	s_ashr_i32 s31, s30, 31
	s_mul_i32 s4, s30, 0xd300000
	s_mul_hi_i32 s2, s30, 0xd300000
	s_add_u32 s28, s53, s4
	s_addc_u32 s29, s54, s2
	s_cmpk_gt_i32 s42, 0x157f
	s_mov_b64 s[40:41], -1
	s_cbranch_scc0 .LBB0_321
	s_cmpk_gt_u32 s42, 0x203f
	s_cbranch_scc1 .LBB0_313
	s_getpc_b64 s[98:99]
